# P5 prompt rows: conv weights/bias loaded once before the row loop; a row's 16 PL loads issued together with its PR loads (one memory round trip per row instead of five)
# speedup vs baseline: 1.0128x; 1.0023x over previous
; __device__ __forceinline__ f32x4 unpack4(u32x2 u) { return (f32x4){__uint_as_float(u.x << 16), __uint_as_float(u.x & 0xffff0000u), __uint_as_float(u.y << 16), __uint_as_float(u.y & 0xffff0000u)}; }
; __device__ __forceinline__ u32x2 pack4(f32x4 v) { u32x2 r; r.x = cvt_pk_bf16(v.x, v.y); r.y = cvt_pk_bf16(v.z, v.w); return r; }
; __device__ __forceinline__ float sigm(float x) { return 1.0f / (1.0f + __expf(-x)); }
; __device__ __forceinline__ float tanh_(float x) { float e = __expf(2.0f * x); return 1.0f - 2.0f / (e + 1.0f); }
; template <int ph>
; __device__ __forceinline__ void run_phase(const Args& args, LAS unsigned char* lds, const int G, const int bx, const bool fin = true) {
;     ...
;         for (int row = gw; row < MT; row += ngw) {
;             const bool smp = row >= MP; const int t = row & (T - 1), b = row >> 11, si = row - MP;
;             if (!smp) {
;                 const int r1 = t >= 1 ? row - 1 : row, r2 = t >= 2 ? row - 2 : row, r3 = t >= 3 ? row - 3 : row;
;                 const float m1 = t >= 1 ? 1.f : 0.f, m2 = t >= 2 ? 1.f : 0.f, m3 = t >= 3 ? 1.f : 0.f;
;                 { const int c = 3072 + 4 * lane; const f32x4 p = unpack4(*(const u32x2*)(PR + (size_t)row * RP + c)), pv = unpack4(*(const u32x2*)(PR + (size_t)r1 * RP + c)) * m1;
;                   const f32x4 mu = *(const f32x4*)(shift_mu + c); f32x4 xs = p + (pv - p) * mu;
;                   if (lane < 16) xs = (f32x4){tanh_(xs[0]), tanh_(xs[1]), tanh_(xs[2]), tanh_(xs[3])}; else if (lane >= 32) xs = (f32x4){sigm(xs[0]), sigm(xs[1]), sigm(xs[2]), sigm(xs[3])};
;                   *(u32x2*)(LB + (size_t)row * 256 + 4 * lane) = pack4(xs); }
;                 f32x4 p3v[4];
; #pragma unroll
;                 for (int j = 0; j < 4; ++j) { const int c = 256 * j + 4 * lane;
;                     const f32x4 p3 = unpack4(*(const u32x2*)(PL + (size_t)row * D + c)), p2 = unpack4(*(const u32x2*)(PL + (size_t)r1 * D + c)) * m1,
;                                 p1 = unpack4(*(const u32x2*)(PL + (size_t)r2 * D + c)) * m2, p0 = unpack4(*(const u32x2*)(PL + (size_t)r3 * D + c)) * m3;
;                     const f32x4 xc = *(const f32x4*)(conv_b + c) + *(const f32x4*)(conv_w + c) * p0 + *(const f32x4*)(conv_w + D + c) * p1 + *(const f32x4*)(conv_w + 2 * D + c) * p2 + *(const f32x4*)(conv_w + 3 * D + c) * p3;
.LBB0_679:
	s_cmp_lt_i32 s96, 6
	s_cselect_b64 s[0:1], -1, 0
	s_cmp_gt_i32 s97, 5
	s_cselect_b64 s[2:3], -1, 0
	s_and_b64 s[0:1], s[0:1], s[2:3]
	s_andn2_b64 vcc, exec, s[0:1]
	s_cbranch_vccnz .LBB0_761
	v_mov_b32_e32 v0, v202
	s_lshl_b32 s20, s81, 3
	v_readfirstlane_b32 s0, v0
	s_ashr_i32 s1, s0, 6
	s_add_i32 s0, s1, s20
	s_cmpk_gt_i32 s0, 0x407f
	s_cbranch_scc1 .LBB0_707
	s_lshl_b32 s10, s33, 3
	s_add_u32 s6, s34, 0x9e00000
	v_readlane_b32 s64, v229, 32
	s_addc_u32 s7, s35, 0
	v_readlane_b32 s70, v229, 38
	v_and_b32_e32 v1, 63, v0
	v_readlane_b32 s65, v229, 33
	v_readlane_b32 s66, v229, 34
	v_readlane_b32 s67, v229, 35
	v_readlane_b32 s71, v229, 39
	s_add_u32 s24, s70, 0x1000
	v_lshlrev_b32_e32 v0, 2, v1
	s_addc_u32 s25, s71, 0
	v_readlane_b32 s52, v229, 48
	v_or_b32_e32 v16, 0xc00, v0
	s_add_u32 s26, s70, 0x2000
	v_readlane_b32 s53, v229, 49
	v_readlane_b32 s54, v229, 50
	v_readlane_b32 s55, v229, 51
	v_readlane_b32 s56, v229, 52
	v_readlane_b32 s57, v229, 53
	v_readlane_b32 s58, v229, 54
	v_readlane_b32 s59, v229, 55
	v_readlane_b32 s60, v229, 56
	v_readlane_b32 s61, v229, 57
	v_readlane_b32 s62, v229, 58
	v_readlane_b32 s63, v229, 59
	v_readlane_b32 s64, v229, 60
	v_readlane_b32 s65, v229, 61
	v_readlane_b32 s66, v229, 62
	v_readlane_b32 s67, v229, 63
	v_mov_b32_e32 v19, 0
	v_lshlrev_b32_e32 v18, 1, v16
	s_addc_u32 s27, s71, 0
	s_mov_b64 s[30:31], s[66:67]
	v_readlane_b32 s52, v229, 0
	v_lshl_add_u64 v[20:21], s[6:7], 0, v[18:19]
	v_lshlrev_b32_e32 v18, 2, v16
	s_add_u32 s28, s70, 0x3000
	v_lshlrev_b32_e32 v6, 4, v1
	v_readlane_b32 s64, v229, 12
	v_readlane_b32 s65, v229, 13
	v_lshl_add_u64 v[22:23], s[36:37], 0, v[18:19]
	s_addc_u32 s29, s71, 0
	v_lshl_add_u64 v[28:29], s[64:65], 0, v[18:19]
	v_or_b32_e32 v18, 0x400, v6
	v_lshl_add_u64 v[40:41], s[24:25], 0, v[18:19]
	v_lshl_add_u64 v[42:43], s[26:27], 0, v[18:19]
	v_lshl_add_u64 v[44:45], s[28:29], 0, v[18:19]
	v_or_b32_e32 v18, 0x800, v6
	v_lshlrev_b32_e32 v2, 3, v1
	v_mov_b32_e32 v3, v19
	v_mov_b32_e32 v7, v19
	v_lshl_add_u64 v[46:47], s[24:25], 0, v[18:19]
	v_lshl_add_u64 v[48:49], s[26:27], 0, v[18:19]
	v_lshl_add_u64 v[50:51], s[28:29], 0, v[18:19]
	v_or_b32_e32 v18, 0xc00, v6
	v_lshl_add_u64 v[4:5], s[34:35], 0, v[2:3]
	v_lshl_add_u64 v[34:35], s[24:25], 0, v[6:7]
	v_lshl_add_u64 v[52:53], s[24:25], 0, v[18:19]
	s_mov_b64 s[24:25], 0x10700000
	s_add_u32 s11, s30, 0x74da000
	v_lshl_add_u64 v[58:59], v[4:5], 0, s[24:25]
	s_mov_b64 s[24:25], 0x7d80000
	s_addc_u32 s13, s31, 0
	v_lshl_add_u64 v[60:61], v[4:5], 0, s[24:25]
	s_ashr_i32 s21, s1, 31
	s_ashr_i32 s24, s20, 31
	s_add_u32 s1, s1, s20
	s_addc_u32 s20, s21, s24
	s_mulk_i32 s20, 0x1a00
	s_mul_hi_u32 s21, s1, 0x1a00
	s_add_i32 s21, s21, s20
	s_mulk_i32 s1, 0x1a00
	s_add_u32 s20, s34, s1
	s_addc_u32 s21, s35, s21
	s_mov_b64 s[22:23], 0x9e00000
	v_lshl_add_u64 v[2:3], s[20:21], 0, v[2:3]
	s_mov_b64 s[8:9], 0x1ee00000
	v_readlane_b32 s72, v229, 40
	v_readlane_b32 s73, v229, 41
	v_lshl_add_u64 v[8:9], s[30:31], 0, v[6:7]
	s_mov_b64 s[40:41], 0x52a2000
	v_lshl_add_u64 v[62:63], v[2:3], 0, s[22:23]
	s_mov_b64 s[24:25], 0x5280000
	v_lshl_add_u64 v[66:67], v[4:5], 0, s[22:23]
	s_mov_b64 s[22:23], 0x72ba000
	v_cmp_lt_u32_e64 s[2:3], 15, v1
	v_cmp_lt_u32_e64 s[4:5], 31, v1
	v_lshl_add_u64 v[24:25], v[4:5], 0, s[8:9]
	s_mov_b64 s[8:9], 0x1000
	s_mov_b64 s[14:15], 0x2000
	v_lshl_add_u64 v[26:27], v[8:9], 0, s[40:41]
	v_lshl_add_u64 v[30:31], s[72:73], 0, v[6:7]
	v_lshl_add_u64 v[32:33], s[70:71], 0, v[6:7]
	v_lshl_add_u64 v[36:37], s[26:27], 0, v[6:7]
	v_lshl_add_u64 v[38:39], s[28:29], 0, v[6:7]
	v_lshl_add_u64 v[54:55], s[26:27], 0, v[18:19]
	v_lshl_add_u64 v[56:57], s[28:29], 0, v[18:19]
	v_or_b32_e32 v17, 0xffffff00, v0
	s_mul_i32 s20, s33, 0xd000
	s_mul_hi_i32 s21, s10, 0x1a00
	v_lshl_add_u64 v[64:65], v[8:9], 0, s[24:25]
	v_lshl_add_u64 v[68:69], v[8:9], 0, s[22:23]
	s_add_i32 s46, s0, 0xffffc000
	s_mov_b32 s1, 0
	s_mov_b64 s[22:23], 0x200
	s_mov_b64 s[24:25], 0x400
	s_movk_i32 s47, 0xbff
	v_lshlrev_b32_e32 v18, 2, v0
	s_movk_i32 s52, 0x2000
	v_mov_b32_e32 v73, 0x1a00
	v_mov_b32_e32 v75, 0x3400
	v_readlane_b32 s68, v229, 36
	v_readlane_b32 s69, v229, 37
	v_readlane_b32 s74, v229, 42
	v_readlane_b32 s75, v229, 43
	v_readlane_b32 s76, v229, 44
	v_readlane_b32 s77, v229, 45
	v_readlane_b32 s78, v229, 46
	v_readlane_b32 s79, v229, 47
	v_readlane_b32 s53, v229, 1
	v_readlane_b32 s54, v229, 2
	v_readlane_b32 s55, v229, 3
	v_readlane_b32 s56, v229, 4
	v_readlane_b32 s57, v229, 5
	v_readlane_b32 s58, v229, 6
	v_readlane_b32 s59, v229, 7
	v_readlane_b32 s60, v229, 8
	v_readlane_b32 s61, v229, 9
	v_readlane_b32 s62, v229, 10
	v_readlane_b32 s63, v229, 11
	v_readlane_b32 s66, v229, 14
	v_readlane_b32 s67, v229, 15
	global_load_dwordx4 v[126:129], v[30:31], off
	global_load_dwordx4 v[130:133], v[32:33], off
	global_load_dwordx4 v[134:137], v[34:35], off
	global_load_dwordx4 v[138:141], v[36:37], off
	global_load_dwordx4 v[142:145], v[38:39], off
	global_load_dwordx4 v[146:149], v[30:31], off offset:1024
	global_load_dwordx4 v[150:153], v[32:33], off offset:1024
	global_load_dwordx4 v[154:157], v[40:41], off
	global_load_dwordx4 v[158:161], v[42:43], off
	global_load_dwordx4 v[162:165], v[44:45], off
	global_load_dwordx4 v[166:169], v[30:31], off offset:2048
	global_load_dwordx4 v[170:173], v[32:33], off offset:2048
	global_load_dwordx4 v[174:177], v[46:47], off
	global_load_dwordx4 v[178:181], v[48:49], off
	global_load_dwordx4 v[182:185], v[50:51], off
	global_load_dwordx4 v[186:189], v[30:31], off offset:3072
	global_load_dwordx4 v[190:193], v[32:33], off offset:3072
	global_load_dwordx4 v[194:197], v[52:53], off
	global_load_dwordx4 v[198:201], v[54:55], off
	global_load_dwordx4 v[204:207], v[56:57], off
	s_waitcnt vmcnt(0)
	s_branch .LBB0_683

; __device__ __forceinline__ f32x4 unpack4(u32x2 u) { return (f32x4){__uint_as_float(u.x << 16), __uint_as_float(u.x & 0xffff0000u), __uint_as_float(u.y << 16), __uint_as_float(u.y & 0xffff0000u)}; }
; __device__ __forceinline__ u32x2 pack4(f32x4 v) { u32x2 r; r.x = cvt_pk_bf16(v.x, v.y); r.y = cvt_pk_bf16(v.z, v.w); return r; }
; __device__ __forceinline__ float sigm(float x) { return 1.0f / (1.0f + __expf(-x)); }
; __device__ __forceinline__ float tanh_(float x) { float e = __expf(2.0f * x); return 1.0f - 2.0f / (e + 1.0f); }
; template <int ph>
; __device__ __forceinline__ void run_phase(const Args& args, LAS unsigned char* lds, const int G, const int bx, const bool fin = true) {
;     ...
;                 const int r1 = t >= 1 ? row - 1 : row, r2 = t >= 2 ? row - 2 : row, r3 = t >= 3 ? row - 3 : row;
;                 const float m1 = t >= 1 ? 1.f : 0.f, m2 = t >= 2 ? 1.f : 0.f, m3 = t >= 3 ? 1.f : 0.f;
;                 { const int c = 3072 + 4 * lane; const f32x4 p = unpack4(*(const u32x2*)(PR + (size_t)row * RP + c)), pv = unpack4(*(const u32x2*)(PR + (size_t)r1 * RP + c)) * m1;
;                   const f32x4 mu = *(const f32x4*)(shift_mu + c); f32x4 xs = p + (pv - p) * mu;
;                   if (lane < 16) xs = (f32x4){tanh_(xs[0]), tanh_(xs[1]), tanh_(xs[2]), tanh_(xs[3])}; else if (lane >= 32) xs = (f32x4){sigm(xs[0]), sigm(xs[1]), sigm(xs[2]), sigm(xs[3])};
;                   *(u32x2*)(LB + (size_t)row * 256 + 4 * lane) = pack4(xs); }
;                 f32x4 p3v[4];
; #pragma unroll
;                 for (int j = 0; j < 4; ++j) { const int c = 256 * j + 4 * lane;
;                     const f32x4 p3 = unpack4(*(const u32x2*)(PL + (size_t)row * D + c)), p2 = unpack4(*(const u32x2*)(PL + (size_t)r1 * D + c)) * m1,
;                                 p1 = unpack4(*(const u32x2*)(PL + (size_t)r2 * D + c)) * m2, p0 = unpack4(*(const u32x2*)(PL + (size_t)r3 * D + c)) * m3;
.LBB0_683:
	s_mov_b64 s[28:29], -1
	s_cmpk_gt_i32 s0, 0x3fff
	s_mul_i32 s26, s0, 0x1a00
	v_lshlrev_b32_e32 v80, 1, v16
	s_cbranch_scc1 .LBB0_697
	s_and_b32 s27, s0, 0x7ff
	s_cmp_lg_u32 s27, 0
	s_cselect_b64 s[28:29], -1, 0
	s_cmp_lg_u64 s[28:29], 0
	v_cndmask_b32_e64 v70, 0, 1.0, s[28:29]
	s_subb_u32 s28, s0, 0
	s_mul_hi_i32 s29, s0, 0x1a00
	s_add_u32 s40, s6, s26
	s_addc_u32 s41, s7, s29
	global_load_dwordx2 v[0:1], v80, s[40:41]
	v_mad_i64_i32 v[2:3], s[40:41], s28, v73, v[20:21]
	global_load_dwordx2 v[6:7], v[2:3], off
	s_nop 0
	global_load_dwordx4 v[2:5], v[22:23], off
	s_bfe_i64 s[98:99], s[0:1], 0x200000
	s_lshl_b64 s[98:99], s[98:99], 11
	v_lshl_add_u64 v[242:243], v[58:59], 0, s[98:99]
	s_ashr_i32 s99, s28, 31
	s_mov_b32 s98, s28
	s_lshl_b64 s[98:99], s[98:99], 11
	v_lshl_add_u64 v[244:245], v[58:59], 0, s[98:99]
	s_add_i32 s100, s0, -2
	s_cmp_gt_u32 s27, 1
	s_cselect_b32 s98, s100, s0
	s_ashr_i32 s99, s98, 31
	s_lshl_b64 s[98:99], s[98:99], 11
	v_lshl_add_u64 v[246:247], v[58:59], 0, s[98:99]
	s_add_i32 s100, s0, -3
	s_cmp_gt_u32 s27, 2
	s_cselect_b32 s98, s100, s0
	s_ashr_i32 s99, s98, 31
	s_lshl_b64 s[98:99], s[98:99], 11
	v_lshl_add_u64 v[248:249], v[58:59], 0, s[98:99]
	global_load_dwordx2 v[208:209], v[242:243], off
	global_load_dwordx2 v[210:211], v[244:245], off
	global_load_dwordx2 v[212:213], v[246:247], off
	global_load_dwordx2 v[214:215], v[248:249], off
	global_load_dwordx2 v[216:217], v[242:243], off offset:512
	global_load_dwordx2 v[218:219], v[242:243], off offset:1024
	global_load_dwordx2 v[220:221], v[242:243], off offset:1536
	global_load_dwordx2 v[222:223], v[244:245], off offset:512
	global_load_dwordx2 v[224:225], v[244:245], off offset:1024
	global_load_dwordx2 v[226:227], v[244:245], off offset:1536
	global_load_dwordx2 v[230:231], v[246:247], off offset:512
	global_load_dwordx2 v[232:233], v[246:247], off offset:1024
	global_load_dwordx2 v[234:235], v[246:247], off offset:1536
	global_load_dwordx2 v[236:237], v[248:249], off offset:512
	global_load_dwordx2 v[238:239], v[248:249], off offset:1024
	global_load_dwordx2 v[240:241], v[248:249], off offset:1536
	s_waitcnt vmcnt(16)
	v_lshlrev_b32_e32 v8, 16, v0
	v_and_b32_e32 v9, 0xffff0000, v0
	v_lshlrev_b32_e32 v0, 16, v1
	v_and_b32_e32 v1, 0xffff0000, v1
	v_lshlrev_b32_e32 v10, 16, v6
	v_and_b32_e32 v11, 0xffff0000, v6
	v_lshlrev_b32_e32 v6, 16, v7
	v_and_b32_e32 v7, 0xffff0000, v7
	v_xor_b32_e32 v13, 0x80000000, v9
	v_xor_b32_e32 v12, 0x80000000, v8
	v_xor_b32_e32 v15, 0x80000000, v1
	v_xor_b32_e32 v14, 0x80000000, v0
	v_pk_fma_f32 v[10:11], v[70:71], v[10:11], v[12:13] op_sel_hi:[0,1,1]
	v_pk_fma_f32 v[6:7], v[70:71], v[6:7], v[14:15] op_sel_hi:[0,1,1]
	v_pk_fma_f32 v[0:1], v[4:5], v[6:7], v[0:1]
	v_pk_fma_f32 v[2:3], v[2:3], v[10:11], v[8:9]
	s_and_saveexec_b64 s[40:41], s[2:3]
	s_xor_b64 s[40:41], exec, s[40:41]
	s_cbranch_execz .LBB0_688
	s_and_saveexec_b64 s[44:45], s[4:5]
	s_cbranch_execz .LBB0_687
	v_mul_f32_e32 v0, 0xbfb8aa3b, v0
	v_mul_f32_e32 v1, 0xbfb8aa3b, v1
	v_exp_f32_e32 v0, v0
	v_exp_f32_e32 v1, v1
	v_mul_f32_e32 v2, 0xbfb8aa3b, v2
	v_mul_f32_e32 v3, 0xbfb8aa3b, v3
	v_exp_f32_e32 v2, v2
	v_pk_add_f32 v[0:1], v[0:1], 1.0 op_sel_hi:[1,0]
	v_exp_f32_e32 v3, v3
	v_div_scale_f32 v4, s[54:55], v1, v1, 1.0
	v_rcp_f32_e32 v5, v4
	v_pk_add_f32 v[2:3], v[2:3], 1.0 op_sel_hi:[1,0]
	v_fma_f32 v6, -v4, v5, 1.0
	v_fmac_f32_e32 v5, v6, v5
	v_div_scale_f32 v6, vcc, 1.0, v1, 1.0
	v_mul_f32_e32 v7, v6, v5
	v_fma_f32 v8, -v4, v7, v6
	v_fmac_f32_e32 v7, v8, v5
	v_fma_f32 v4, -v4, v7, v6
	v_div_scale_f32 v6, s[54:55], v0, v0, 1.0
	v_rcp_f32_e32 v8, v6
	v_div_fmas_f32 v4, v4, v5, v7
	v_div_fixup_f32 v1, v4, v1, 1.0
	v_fma_f32 v4, -v6, v8, 1.0
	v_fmac_f32_e32 v8, v4, v8
	v_div_scale_f32 v4, vcc, 1.0, v0, 1.0
	v_mul_f32_e32 v5, v4, v8
	v_fma_f32 v7, -v6, v5, v4
	v_fmac_f32_e32 v5, v7, v8
	v_fma_f32 v4, -v6, v5, v4
	v_div_scale_f32 v6, s[54:55], v3, v3, 1.0
	v_rcp_f32_e32 v7, v6
	v_div_fmas_f32 v4, v4, v8, v5
	v_div_fixup_f32 v0, v4, v0, 1.0
	v_fma_f32 v4, -v6, v7, 1.0
	v_fmac_f32_e32 v7, v4, v7
	v_div_scale_f32 v4, vcc, 1.0, v3, 1.0
	v_mul_f32_e32 v5, v4, v7
	v_fma_f32 v8, -v6, v5, v4
	v_fmac_f32_e32 v5, v8, v7
	v_fma_f32 v4, -v6, v5, v4
	v_div_scale_f32 v6, s[54:55], v2, v2, 1.0
	v_rcp_f32_e32 v8, v6
	v_div_fmas_f32 v4, v4, v7, v5
	v_div_fixup_f32 v3, v4, v3, 1.0
	v_fma_f32 v4, -v6, v8, 1.0
	v_fmac_f32_e32 v8, v4, v8
	v_div_scale_f32 v4, vcc, 1.0, v2, 1.0
	v_mul_f32_e32 v5, v4, v8
	v_fma_f32 v7, -v6, v5, v4
	v_fmac_f32_e32 v5, v7, v8
	v_fma_f32 v4, -v6, v5, v4
	v_div_fmas_f32 v4, v4, v8, v5
	v_div_fixup_f32 v2, v4, v2, 1.0

; __device__ __forceinline__ f32x4 unpack4(u32x2 u) { return (f32x4){__uint_as_float(u.x << 16), __uint_as_float(u.x & 0xffff0000u), __uint_as_float(u.y << 16), __uint_as_float(u.y & 0xffff0000u)}; }
; __device__ __forceinline__ u32x2 pack4(f32x4 v) { u32x2 r; r.x = cvt_pk_bf16(v.x, v.y); r.y = cvt_pk_bf16(v.z, v.w); return r; }
; __device__ __forceinline__ float sigm(float x) { return 1.0f / (1.0f + __expf(-x)); }
; __device__ __forceinline__ float tanh_(float x) { float e = __expf(2.0f * x); return 1.0f - 2.0f / (e + 1.0f); }
; template <int ph>
; __device__ __forceinline__ void run_phase(const Args& args, LAS unsigned char* lds, const int G, const int bx, const bool fin = true) {
;     ...
;                 const int r1 = t >= 1 ? row - 1 : row, r2 = t >= 2 ? row - 2 : row, r3 = t >= 3 ? row - 3 : row;
;                 const float m1 = t >= 1 ? 1.f : 0.f, m2 = t >= 2 ? 1.f : 0.f, m3 = t >= 3 ? 1.f : 0.f;
;                 { const int c = 3072 + 4 * lane; const f32x4 p = unpack4(*(const u32x2*)(PR + (size_t)row * RP + c)), pv = unpack4(*(const u32x2*)(PR + (size_t)r1 * RP + c)) * m1;
;                   const f32x4 mu = *(const f32x4*)(shift_mu + c); f32x4 xs = p + (pv - p) * mu;
;                   if (lane < 16) xs = (f32x4){tanh_(xs[0]), tanh_(xs[1]), tanh_(xs[2]), tanh_(xs[3])}; else if (lane >= 32) xs = (f32x4){sigm(xs[0]), sigm(xs[1]), sigm(xs[2]), sigm(xs[3])};
;                   *(u32x2*)(LB + (size_t)row * 256 + 4 * lane) = pack4(xs); }
;                 f32x4 p3v[4];
; #pragma unroll
;                 for (int j = 0; j < 4; ++j) { const int c = 256 * j + 4 * lane;
;                     const f32x4 p3 = unpack4(*(const u32x2*)(PL + (size_t)row * D + c)), p2 = unpack4(*(const u32x2*)(PL + (size_t)r1 * D + c)) * m1,
;                                 p1 = unpack4(*(const u32x2*)(PL + (size_t)r2 * D + c)) * m2, p0 = unpack4(*(const u32x2*)(PL + (size_t)r3 * D + c)) * m3;
;                     const f32x4 xc = *(const f32x4*)(conv_b + c) + *(const f32x4*)(conv_w + c) * p0 + *(const f32x4*)(conv_w + D + c) * p1 + *(const f32x4*)(conv_w + 2 * D + c) * p2 + *(const f32x4*)(conv_w + 3 * D + c) * p3;
;                     *(u32x2*)(XC + (size_t)row * D + c) = pack4(xc); p3v[j] = p3; }
.LBB0_690:
	s_or_b64 exec, exec, s[40:41]
	s_bfe_i64 s[40:41], s[0:1], 0x200000
	s_ashr_i32 s29, s28, 31
	s_add_i32 s53, s0, -2
	s_cmp_gt_u32 s27, 1
	s_cselect_b64 s[44:45], -1, 0
	v_cndmask_b32_e64 v74, 0, 1.0, s[44:45]
	s_and_b64 s[44:45], s[44:45], exec
	s_cselect_b32 s44, s53, s0
	s_add_i32 s45, s0, -3
	s_cmp_gt_u32 s27, 2
	s_cselect_b64 s[54:55], -1, 0
	v_cndmask_b32_e64 v72, 0, 1.0, s[54:55]
	s_and_b64 s[54:55], s[54:55], exec
	s_cselect_b32 s54, s45, s0
	s_lshl_b64 s[56:57], s[40:41], 9
	s_lshl_b64 s[28:29], s[28:29], 11
	s_ashr_i32 s45, s44, 31
	v_cvt_pk_bf16_f32 v2, v2, v3
	v_cvt_pk_bf16_f32 v3, v0, v1
	v_lshl_add_u64 v[0:1], v[24:25], 0, s[56:57]
	s_lshl_b64 s[40:41], s[40:41], 11
	v_lshl_add_u64 v[14:15], v[58:59], 0, s[28:29]
	s_lshl_b64 s[28:29], s[44:45], 11
	global_store_dwordx2 v[0:1], v[2:3], off
	v_lshl_add_u64 v[0:1], v[58:59], 0, s[40:41]
	v_lshl_add_u64 v[94:95], v[58:59], 0, s[28:29]
	s_ashr_i32 s55, s54, 31
	s_lshl_b64 s[28:29], s[54:55], 11
	v_lshl_add_u64 v[98:99], v[58:59], 0, s[28:29]
	s_nop 0
	v_mov_b32_e32 v71, v70
	v_mov_b32_e32 v78, v70
	v_mov_b32_e32 v79, v70
	v_lshl_add_u64 v[76:77], v[60:61], 0, s[40:41]
	s_ashr_i32 s28, s0, 11
	s_cmpk_lt_u32 s27, 0x7fd
	s_waitcnt vmcnt(16)
	v_lshlrev_b32_e32 v0, 16, v208
	s_waitcnt vmcnt(13)
	v_lshlrev_b32_e32 v124, 16, v214
	v_and_b32_e32 v125, 0xffff0000, v214
	v_lshlrev_b32_e32 v100, 16, v215
	v_and_b32_e32 v101, 0xffff0000, v215
	v_lshlrev_b32_e32 v98, 16, v212
	v_and_b32_e32 v99, 0xffff0000, v212
	v_lshlrev_b32_e32 v96, 16, v213
	v_and_b32_e32 v97, 0xffff0000, v213
	v_pk_mul_f32 v[100:101], v[72:73], v[100:101] op_sel_hi:[0,1]
	v_pk_mul_f32 v[124:125], v[72:73], v[124:125] op_sel_hi:[0,1]
	v_lshlrev_b32_e32 v14, 16, v210
	v_and_b32_e32 v15, 0xffff0000, v210
	v_lshlrev_b32_e32 v4, 16, v211
	v_and_b32_e32 v5, 0xffff0000, v211
	v_pk_mul_f32 v[98:99], v[74:75], v[98:99] op_sel_hi:[0,1]
	v_pk_mul_f32 v[96:97], v[74:75], v[96:97] op_sel_hi:[0,1]
	v_pk_fma_f32 v[6:7], v[130:131], v[124:125], v[126:127]
	v_pk_fma_f32 v[8:9], v[132:133], v[100:101], v[128:129]
	v_pk_mul_f32 v[4:5], v[78:79], v[4:5]
	v_pk_mul_f32 v[14:15], v[70:71], v[14:15]
	v_pk_fma_f32 v[8:9], v[136:137], v[96:97], v[8:9]
	v_pk_fma_f32 v[6:7], v[134:135], v[98:99], v[6:7]
	v_and_b32_e32 v1, 0xffff0000, v208
	v_lshlrev_b32_e32 v2, 16, v209
	v_and_b32_e32 v3, 0xffff0000, v209
	v_pk_fma_f32 v[6:7], v[138:139], v[14:15], v[6:7]
	v_pk_fma_f32 v[4:5], v[140:141], v[4:5], v[8:9]
	v_pk_fma_f32 v[6:7], v[142:143], v[0:1], v[6:7]
	v_pk_fma_f32 v[4:5], v[144:145], v[2:3], v[4:5]
	v_cvt_pk_bf16_f32 v6, v6, v7
	v_cvt_pk_bf16_f32 v7, v4, v5
	global_store_dwordx2 v[76:77], v[6:7], off
	s_waitcnt vmcnt(10)
	v_lshlrev_b32_e32 v96, 16, v222
	v_and_b32_e32 v97, 0xffff0000, v222
	v_lshlrev_b32_e32 v98, 16, v223
	v_and_b32_e32 v99, 0xffff0000, v223
	s_waitcnt vmcnt(4)
	v_lshlrev_b32_e32 v108, 16, v236
	v_and_b32_e32 v109, 0xffff0000, v236
	v_lshlrev_b32_e32 v94, 16, v237
	v_and_b32_e32 v95, 0xffff0000, v237
	v_lshlrev_b32_e32 v4, 16, v216
	v_and_b32_e32 v5, 0xffff0000, v216
	v_lshlrev_b32_e32 v6, 16, v217
	v_and_b32_e32 v7, 0xffff0000, v217
	v_lshlrev_b32_e32 v100, 16, v230
	v_and_b32_e32 v101, 0xffff0000, v230
	v_lshlrev_b32_e32 v102, 16, v231
	v_and_b32_e32 v103, 0xffff0000, v231
	v_pk_mul_f32 v[94:95], v[72:73], v[94:95] op_sel_hi:[0,1]
	v_pk_mul_f32 v[108:109], v[72:73], v[108:109] op_sel_hi:[0,1]
	v_pk_mul_f32 v[100:101], v[74:75], v[100:101] op_sel_hi:[0,1]
	v_pk_mul_f32 v[102:103], v[74:75], v[102:103] op_sel_hi:[0,1]
	v_pk_mul_f32 v[98:99], v[78:79], v[98:99]
	v_pk_mul_f32 v[96:97], v[70:71], v[96:97]
	v_pk_fma_f32 v[8:9], v[150:151], v[108:109], v[146:147]
	v_pk_fma_f32 v[10:11], v[152:153], v[94:95], v[148:149]
	v_pk_fma_f32 v[8:9], v[154:155], v[100:101], v[8:9]
	v_pk_fma_f32 v[10:11], v[156:157], v[102:103], v[10:11]
	v_pk_fma_f32 v[8:9], v[158:159], v[96:97], v[8:9]
	v_pk_fma_f32 v[10:11], v[160:161], v[98:99], v[10:11]
	v_pk_fma_f32 v[8:9], v[162:163], v[4:5], v[8:9]
	v_pk_fma_f32 v[10:11], v[164:165], v[6:7], v[10:11]
	v_cvt_pk_bf16_f32 v8, v8, v9
	v_cvt_pk_bf16_f32 v9, v10, v11
	global_store_dwordx2 v[76:77], v[8:9], off offset:512
	v_lshlrev_b32_e32 v98, 16, v224
	v_and_b32_e32 v99, 0xffff0000, v224
	v_lshlrev_b32_e32 v100, 16, v225
	v_and_b32_e32 v101, 0xffff0000, v225
	s_waitcnt vmcnt(4)
; __device__ __forceinline__ f32x4 unpack4(u32x2 u) { return (f32x4){__uint_as_float(u.x << 16), __uint_as_float(u.x & 0xffff0000u), __uint_as_float(u.y << 16), __uint_as_float(u.y & 0xffff0000u)}; }
; __device__ __forceinline__ u32x2 pack4(f32x4 v) { u32x2 r; r.x = cvt_pk_bf16(v.x, v.y); r.y = cvt_pk_bf16(v.z, v.w); return r; }
; template <int ph>
; __device__ __forceinline__ void run_phase(const Args& args, LAS unsigned char* lds, const int G, const int bx, const bool fin = true) {
;     ...
;                 for (int j = 0; j < 4; ++j) { const int c = 256 * j + 4 * lane;
;                     const f32x4 p3 = unpack4(*(const u32x2*)(PL + (size_t)row * D + c)), p2 = unpack4(*(const u32x2*)(PL + (size_t)r1 * D + c)) * m1,
;                                 p1 = unpack4(*(const u32x2*)(PL + (size_t)r2 * D + c)) * m2, p0 = unpack4(*(const u32x2*)(PL + (size_t)r3 * D + c)) * m3;
;                     const f32x4 xc = *(const f32x4*)(conv_b + c) + *(const f32x4*)(conv_w + c) * p0 + *(const f32x4*)(conv_w + D + c) * p1 + *(const f32x4*)(conv_w + 2 * D + c) * p2 + *(const f32x4*)(conv_w + 3 * D + c) * p3;
;                     *(u32x2*)(XC + (size_t)row * D + c) = pack4(xc); p3v[j] = p3; }
;                 if (t >= T - 3) {
; #pragma unroll
;                     for (int j = 0; j < 4; ++j) *(f32x4*)(out + O_PCONV + ((size_t)b * 3 + (t - (T - 3))) * D + 256 * j + 4 * lane) = p3v[j];
;                 }
	v_lshlrev_b32_e32 v108, 16, v238
	v_and_b32_e32 v109, 0xffff0000, v238
	v_lshlrev_b32_e32 v110, 16, v239
	v_and_b32_e32 v111, 0xffff0000, v239
	v_lshlrev_b32_e32 v8, 16, v218
	v_and_b32_e32 v9, 0xffff0000, v218
	v_lshlrev_b32_e32 v10, 16, v219
	v_and_b32_e32 v11, 0xffff0000, v219
	v_lshlrev_b32_e32 v102, 16, v232
	v_and_b32_e32 v103, 0xffff0000, v232
	v_lshlrev_b32_e32 v104, 16, v233
	v_and_b32_e32 v105, 0xffff0000, v233
	v_pk_mul_f32 v[110:111], v[72:73], v[110:111] op_sel_hi:[0,1]
	v_pk_mul_f32 v[108:109], v[72:73], v[108:109] op_sel_hi:[0,1]
	v_pk_mul_f32 v[102:103], v[74:75], v[102:103] op_sel_hi:[0,1]
	v_pk_mul_f32 v[104:105], v[74:75], v[104:105] op_sel_hi:[0,1]
	v_pk_mul_f32 v[100:101], v[78:79], v[100:101]
	v_pk_mul_f32 v[98:99], v[70:71], v[98:99]
	v_pk_fma_f32 v[12:13], v[170:171], v[108:109], v[166:167]
	v_pk_fma_f32 v[14:15], v[172:173], v[110:111], v[168:169]
	v_pk_fma_f32 v[12:13], v[174:175], v[102:103], v[12:13]
	v_pk_fma_f32 v[14:15], v[176:177], v[104:105], v[14:15]
	v_pk_fma_f32 v[12:13], v[178:179], v[98:99], v[12:13]
	v_pk_fma_f32 v[14:15], v[180:181], v[100:101], v[14:15]
	v_pk_fma_f32 v[12:13], v[182:183], v[8:9], v[12:13]
	v_pk_fma_f32 v[14:15], v[184:185], v[10:11], v[14:15]
	v_cvt_pk_bf16_f32 v12, v12, v13
	v_cvt_pk_bf16_f32 v13, v14, v15
	global_store_dwordx2 v[76:77], v[12:13], off offset:1024
	v_lshlrev_b32_e32 v12, 16, v220
	v_and_b32_e32 v13, 0xffff0000, v220
	v_lshlrev_b32_e32 v14, 16, v221
	v_and_b32_e32 v15, 0xffff0000, v221
	v_lshlrev_b32_e32 v102, 16, v226
	v_and_b32_e32 v103, 0xffff0000, v226
	v_lshlrev_b32_e32 v104, 16, v227
	v_and_b32_e32 v105, 0xffff0000, v227
	v_lshlrev_b32_e32 v106, 16, v234
	v_and_b32_e32 v107, 0xffff0000, v234
	v_lshlrev_b32_e32 v108, 16, v235
	v_and_b32_e32 v109, 0xffff0000, v235
	v_pk_mul_f32 v[78:79], v[78:79], v[104:105]
	v_pk_mul_f32 v[70:71], v[70:71], v[102:103]
	v_pk_mul_f32 v[102:103], v[74:75], v[106:107] op_sel_hi:[0,1]
	v_pk_mul_f32 v[104:105], v[74:75], v[108:109] op_sel_hi:[0,1]
	s_waitcnt vmcnt(4)
	v_lshlrev_b32_e32 v106, 16, v240
	v_and_b32_e32 v107, 0xffff0000, v240
	v_lshlrev_b32_e32 v108, 16, v241
	v_and_b32_e32 v109, 0xffff0000, v241
	v_pk_mul_f32 v[108:109], v[72:73], v[108:109] op_sel_hi:[0,1]
	v_pk_mul_f32 v[106:107], v[72:73], v[106:107] op_sel_hi:[0,1]
	s_nop 0
	v_pk_fma_f32 v[82:83], v[190:191], v[106:107], v[186:187]
	v_pk_fma_f32 v[84:85], v[192:193], v[108:109], v[188:189]
	v_pk_fma_f32 v[82:83], v[194:195], v[102:103], v[82:83]
	v_pk_fma_f32 v[84:85], v[196:197], v[104:105], v[84:85]
	v_pk_fma_f32 v[70:71], v[198:199], v[70:71], v[82:83]
	v_pk_fma_f32 v[78:79], v[200:201], v[78:79], v[84:85]
	v_pk_fma_f32 v[70:71], v[204:205], v[12:13], v[70:71]
	v_pk_fma_f32 v[78:79], v[206:207], v[14:15], v[78:79]
	v_cvt_pk_bf16_f32 v70, v70, v71
	v_cvt_pk_bf16_f32 v71, v78, v79
	global_store_dwordx2 v[76:77], v[70:71], off offset:1536
	s_cbranch_scc1 .LBB0_692
	s_mul_i32 s29, s28, 3
	s_ashr_i32 s41, s29, 31
	s_add_i32 s40, s27, 0xfffff803
	s_add_u32 s40, s29, s40
	s_addc_u32 s41, s41, 0
	s_lshl_b64 s[40:41], s[40:41], 12
	v_lshl_add_u64 v[70:71], v[26:27], 0, s[40:41]
	global_store_dwordx4 v[70:71], v[0:3], off
	global_store_dwordx4 v[70:71], v[4:7], off offset:1024
	global_store_dwordx4 v[70:71], v[8:11], off offset:2048
	global_store_dwordx4 v[70:71], v[12:15], off offset:3072

; #define LAS __attribute__((address_space(3)))
; __global__ void __launch_bounds__(NTHR, 2) mega(Args args) {
;     extern __shared__ __attribute__((aligned(16))) unsigned char lds_raw[];
;     LAS unsigned char* lds = (LAS unsigned char*)lds_raw;
	.amdhsa_kernel _Z4mega4Args
		.amdhsa_group_segment_fixed_size 0
		.amdhsa_private_segment_fixed_size 0
		.amdhsa_kernarg_size 592
		.amdhsa_user_sgpr_count 2
		.amdhsa_user_sgpr_dispatch_ptr 0
		.amdhsa_user_sgpr_queue_ptr 0
		.amdhsa_user_sgpr_kernarg_segment_ptr 1
		.amdhsa_user_sgpr_dispatch_id 0
		.amdhsa_user_sgpr_kernarg_preload_length 0
		.amdhsa_user_sgpr_kernarg_preload_offset 0
		.amdhsa_user_sgpr_private_segment_size 0
		.amdhsa_uses_dynamic_stack 0
		.amdhsa_enable_private_segment 0
		.amdhsa_system_sgpr_workgroup_id_x 1
		.amdhsa_system_sgpr_workgroup_id_y 0
		.amdhsa_system_sgpr_workgroup_id_z 0
		.amdhsa_system_sgpr_workgroup_info 0
		.amdhsa_system_vgpr_workitem_id 2
		.amdhsa_next_free_vgpr 250
		.amdhsa_next_free_sgpr 102
		.amdhsa_accum_offset 252
		.amdhsa_reserve_vcc 1
		.amdhsa_float_round_mode_32 0
		.amdhsa_float_round_mode_16_64 0
		.amdhsa_float_denorm_mode_32 3
		.amdhsa_float_denorm_mode_16_64 3
		.amdhsa_dx10_clamp 1
		.amdhsa_ieee_mode 1
		.amdhsa_fp16_overflow 0
		.amdhsa_tg_split 0
		.amdhsa_exception_fp_ieee_invalid_op 0
		.amdhsa_exception_fp_denorm_src 0
		.amdhsa_exception_fp_ieee_div_zero 0
		.amdhsa_exception_fp_ieee_overflow 0
		.amdhsa_exception_fp_ieee_underflow 0
		.amdhsa_exception_fp_ieee_inexact 0
		.amdhsa_exception_int_div_zero 0
	.end_amdhsa_kernel

; #define LAS __attribute__((address_space(3)))
; __global__ void __launch_bounds__(NTHR, 2) mega(Args args) {
;     extern __shared__ __attribute__((aligned(16))) unsigned char lds_raw[];
;     LAS unsigned char* lds = (LAS unsigned char*)lds_raw;
amdhsa.kernels:
  - .agpr_count:     0
    .args:
      - .offset:         0
        .size:           336
        .value_kind:     by_value
      - .offset:         336
        .size:           4
        .value_kind:     hidden_block_count_x
      - .offset:         340
        .size:           4
        .value_kind:     hidden_block_count_y
      - .offset:         344
        .size:           4
        .value_kind:     hidden_block_count_z
      - .offset:         348
        .size:           2
        .value_kind:     hidden_group_size_x
      - .offset:         350
        .size:           2
        .value_kind:     hidden_group_size_y
      - .offset:         352
        .size:           2
        .value_kind:     hidden_group_size_z
      - .offset:         354
        .size:           2
        .value_kind:     hidden_remainder_x
      - .offset:         356
        .size:           2
        .value_kind:     hidden_remainder_y
      - .offset:         358
        .size:           2
        .value_kind:     hidden_remainder_z
      - .offset:         376
        .size:           8
        .value_kind:     hidden_global_offset_x
      - .offset:         384
        .size:           8
        .value_kind:     hidden_global_offset_y
      - .offset:         392
        .size:           8
        .value_kind:     hidden_global_offset_z
      - .offset:         400
        .size:           2
        .value_kind:     hidden_grid_dims
      - .offset:         424
        .size:           8
        .value_kind:     hidden_multigrid_sync_arg
      - .offset:         456
        .size:           4
        .value_kind:     hidden_dynamic_lds_size
    .group_segment_fixed_size: 0
    .kernarg_segment_align: 8
    .kernarg_segment_size: 592
    .language:       OpenCL C
    .language_version:
      - 2
      - 0
    .max_flat_workgroup_size: 512
    .name:           _Z4mega4Args
    .private_segment_fixed_size: 0
    .sgpr_count:     108
    .sgpr_spill_count: 68
    .symbol:         _Z4mega4Args.kd
    .uniform_work_group_size: 1
    .uses_dynamic_stack: false
    .vgpr_count:     250
    .vgpr_spill_count: 0
    .wavefront_size: 64
